# E36: P0 memory-state f32->bf16 copies: all eight loads requested before the first convert/store when gridDim.x==256 (original loops otherwise); on E35
# baseline (speedup 1.0000x reference)
.LBB0_98:
	s_ashr_i32 s3, s2, 31
	s_lshl_b64 s[0:1], s[2:3], 9
	v_ashrrev_i32_e32 v67, 31, v66
	v_lshl_add_u64 v[2:3], s[0:1], 0, v[66:67]
	s_ashr_i32 s7, s88, 31
	s_mov_b32 s6, s88
	s_waitcnt lgkmcnt(0)
	s_mov_b64 s[16:17], 0x40000
	s_lshl_b64 s[0:1], s[6:7], 9
	v_cmp_gt_u64_e32 vcc, s[16:17], v[2:3]
	s_and_saveexec_b64 s[16:17], vcc
	s_cbranch_execz .LBB0_103
	v_lshlrev_b64 v[4:5], 4, v[2:3]
	v_lshl_add_u64 v[6:7], s[82:83], 0, v[4:5]
	v_lshlrev_b64 v[4:5], 5, v[2:3]
	v_readlane_b32 s64, v244, 7
	s_mov_b64 s[18:19], 0x3900000
	v_or_b32_e32 v4, 16, v4
	v_readlane_b32 s76, v244, 19
	v_readlane_b32 s77, v244, 20
	v_lshl_add_u64 v[8:9], v[6:7], 0, s[18:19]
	s_lshl_b64 s[18:19], s[6:7], 13
	v_lshl_add_u64 v[10:11], s[76:77], 0, v[4:5]
	s_lshl_b64 s[24:25], s[6:7], 14
	s_mov_b64 s[26:27], 0
	s_mov_b64 s[28:29], 0x3ffff
	v_mov_b64_e32 v[12:13], v[2:3]
	v_readlane_b32 s65, v244, 8
	v_readlane_b32 s66, v244, 9
	v_readlane_b32 s67, v244, 10
	v_readlane_b32 s68, v244, 11
	v_readlane_b32 s69, v244, 12
	v_readlane_b32 s70, v244, 13
	v_readlane_b32 s71, v244, 14
	v_readlane_b32 s72, v244, 15
	v_readlane_b32 s73, v244, 16
	v_readlane_b32 s74, v244, 17
	v_readlane_b32 s75, v244, 18
	v_readlane_b32 s78, v244, 21
	v_readlane_b32 s79, v244, 22
	s_cmpk_lg_u32 s88, 0x100
	s_cbranch_scc1 .LBB0_100
	v_lshl_add_u64 v[46:47], v[10:11], 0, s[24:25]
	v_lshl_add_u64 v[48:49], s[78:79], 0, v[4:5]
	v_lshl_add_u64 v[50:51], v[48:49], 0, s[24:25]
	global_load_dwordx4 v[14:17], v[10:11], off offset:-16 nt
	global_load_dwordx4 v[18:21], v[10:11], off nt
	global_load_dwordx4 v[22:25], v[46:47], off offset:-16 nt
	global_load_dwordx4 v[26:29], v[46:47], off nt
	global_load_dwordx4 v[30:33], v[48:49], off offset:-16 nt
	global_load_dwordx4 v[34:37], v[48:49], off nt
	global_load_dwordx4 v[38:41], v[50:51], off offset:-16 nt
	global_load_dwordx4 v[42:45], v[50:51], off nt
	s_mov_b64 s[26:27], 0x3d00000
	v_lshl_add_u64 v[52:53], v[8:9], 0, s[18:19]
	v_lshl_add_u64 v[54:55], v[6:7], 0, s[26:27]
	v_lshl_add_u64 v[56:57], v[54:55], 0, s[18:19]
	s_waitcnt vmcnt(6)
	v_cvt_pk_bf16_f32 v14, v14, v15
	v_cvt_pk_bf16_f32 v15, v16, v17
	v_cvt_pk_bf16_f32 v16, v18, v19
	v_cvt_pk_bf16_f32 v17, v20, v21
	global_store_dwordx4 v[8:9], v[14:17], off
	s_waitcnt vmcnt(4)
	v_cvt_pk_bf16_f32 v22, v22, v23
	v_cvt_pk_bf16_f32 v23, v24, v25
	v_cvt_pk_bf16_f32 v24, v26, v27
	v_cvt_pk_bf16_f32 v25, v28, v29
	global_store_dwordx4 v[52:53], v[22:25], off
	s_waitcnt vmcnt(2)
	v_cvt_pk_bf16_f32 v30, v30, v31
	v_cvt_pk_bf16_f32 v31, v32, v33
	v_cvt_pk_bf16_f32 v32, v34, v35
	v_cvt_pk_bf16_f32 v33, v36, v37
	global_store_dwordx4 v[54:55], v[30:33], off
	s_waitcnt vmcnt(0)
	v_cvt_pk_bf16_f32 v38, v38, v39
	v_cvt_pk_bf16_f32 v39, v40, v41
	v_cvt_pk_bf16_f32 v40, v42, v43
	v_cvt_pk_bf16_f32 v41, v44, v45
	global_store_dwordx4 v[56:57], v[38:41], off
	s_branch .LBB0_103
